# out-projection epilogue: non-temporal hint on the x residual loads
# baseline (speedup 1.0000x reference)
.LBB0_594:
	s_lshr_b32 s0, s28, 5
	s_mulk_i32 s0, 0x1800
	s_ashr_i32 s1, s0, 31
	s_lshl_b64 s[0:1], s[0:1], 2
	s_add_u32 s0, s52, s0
	s_addc_u32 s1, s53, s1
	v_lshl_add_u32 v150, s28, 8, v154
	v_lshl_or_b32 v152, s26, 8, v156
	v_lshlrev_b32_e32 v144, 2, v152
	s_add_u32 s26, s0, 0x2000
	s_addc_u32 s27, s1, 0
	s_add_u32 s28, s0, 0x4000
	s_addc_u32 s29, s1, 0
	global_load_dwordx4 v[190:193], v144, s[26:27]
	global_load_dwordx4 v[194:197], v144, s[26:27] offset:16
	global_load_dwordx4 v[198:201], v144, s[26:27] offset:512
	global_load_dwordx4 v[202:205], v144, s[26:27] offset:528
	global_load_dwordx4 v[206:209], v144, s[82:83]
	global_load_dwordx4 v[210:213], v144, s[82:83] offset:16
	global_load_dwordx4 v[214:217], v144, s[82:83] offset:512
	global_load_dwordx4 v[218:221], v144, s[82:83] offset:528
	global_load_dwordx4 v[222:225], v144, s[28:29]
	global_load_dwordx4 v[226:229], v144, s[28:29] offset:16
	global_load_dwordx4 v[230:233], v144, s[28:29] offset:512
	global_load_dwordx4 v[234:237], v144, s[28:29] offset:528
	v_lshl_add_u32 v145, v150, 12, v144
	v_lshrrev_b32_e32 v146, 1, v145
	v_lshlrev_b32_e32 v147, 2, v150
	v_xor_b32_e32 v148, 16, v160
	v_lshlrev_b32_e32 v148, 2, v148
	v_xor_b32_e32 v149, 32, v160
	v_lshlrev_b32_e32 v149, 2, v149
	global_load_dwordx4 v[238:241], v145, s[40:41] nt
	global_load_dwordx4 v[242:245], v145, s[40:41] offset:16 nt
	global_load_dwordx4 v[246:249], v145, s[40:41] offset:512 nt
	global_load_dwordx4 v[162:165], v145, s[40:41] offset:528 nt
	s_add_u32 s0, s40, 0x10000
	s_addc_u32 s1, s41, 0
	global_load_dwordx4 v[166:169], v145, s[0:1] nt
	global_load_dwordx4 v[170:173], v145, s[0:1] offset:16 nt
	global_load_dwordx4 v[174:177], v145, s[0:1] offset:512 nt
	global_load_dwordx4 v[178:181], v145, s[0:1] offset:528 nt
	s_waitcnt vmcnt(4)
	v_pk_add_f32 v[222:223], v[222:223], 1.0 op_sel_hi:[1,0]
	v_pk_add_f32 v[224:225], v[224:225], 1.0 op_sel_hi:[1,0]
	v_pk_add_f32 v[226:227], v[226:227], 1.0 op_sel_hi:[1,0]
	v_pk_add_f32 v[228:229], v[228:229], 1.0 op_sel_hi:[1,0]
	v_pk_add_f32 v[230:231], v[230:231], 1.0 op_sel_hi:[1,0]
	v_pk_add_f32 v[232:233], v[232:233], 1.0 op_sel_hi:[1,0]
	v_pk_add_f32 v[234:235], v[234:235], 1.0 op_sel_hi:[1,0]
	v_pk_add_f32 v[236:237], v[236:237], 1.0 op_sel_hi:[1,0]
	s_add_u32 s26, s72, 0x0
	s_addc_u32 s27, s73, 0
	s_add_u32 s28, s10, 0x0
	s_addc_u32 s29, s11, 0
	v_pk_fma_f32 v[124:125], v[124:125], v[190:191], v[238:239]
	v_pk_fma_f32 v[126:127], v[126:127], v[192:193], v[240:241]
	global_store_dwordx4 v145, v[124:127], s[26:27]
	v_mul_f32_e32 v161, v125, v125
	v_mul_f32_e32 v186, v127, v127
	v_fmac_f32_e32 v161, v124, v124
	v_fmac_f32_e32 v186, v126, v126
	v_add_f32_e32 v187, v161, v186
	v_pk_mul_f32 v[238:239], v[206:207], v[124:125]
	v_pk_mul_f32 v[240:241], v[208:209], v[126:127]
	v_pk_mul_f32 v[238:239], v[222:223], v[238:239]
	v_pk_mul_f32 v[240:241], v[224:225], v[240:241]
	v_cvt_pk_bf16_f32 v182, v238, v239
	v_cvt_pk_bf16_f32 v183, v240, v241
	v_pk_fma_f32 v[120:121], v[120:121], v[194:195], v[242:243]
	v_pk_fma_f32 v[122:123], v[122:123], v[196:197], v[244:245]
	global_store_dwordx4 v145, v[120:123], s[26:27] offset:16
	v_mul_f32_e32 v161, v121, v121
	v_mul_f32_e32 v186, v123, v123
	v_fmac_f32_e32 v161, v120, v120
	v_fmac_f32_e32 v186, v122, v122
	v_add_f32_e32 v161, v161, v186
	v_add_f32_e32 v187, v187, v161
	v_pk_mul_f32 v[242:243], v[210:211], v[120:121]
	v_pk_mul_f32 v[244:245], v[212:213], v[122:123]
	v_pk_mul_f32 v[242:243], v[226:227], v[242:243]
	v_pk_mul_f32 v[244:245], v[228:229], v[244:245]
	v_cvt_pk_bf16_f32 v184, v242, v243
	v_cvt_pk_bf16_f32 v185, v244, v245
	global_store_dwordx4 v146, v[182:185], s[28:29]
	v_pk_fma_f32 v[116:117], v[116:117], v[198:199], v[246:247]
	v_pk_fma_f32 v[118:119], v[118:119], v[200:201], v[248:249]
	global_store_dwordx4 v145, v[116:119], s[26:27] offset:512
	v_mul_f32_e32 v161, v117, v117
	v_mul_f32_e32 v186, v119, v119
	v_fmac_f32_e32 v161, v116, v116
	v_fmac_f32_e32 v186, v118, v118
	v_add_f32_e32 v161, v161, v186
	v_add_f32_e32 v187, v187, v161
	v_pk_mul_f32 v[246:247], v[214:215], v[116:117]
	v_pk_mul_f32 v[248:249], v[216:217], v[118:119]
	v_pk_mul_f32 v[246:247], v[230:231], v[246:247]
	v_pk_mul_f32 v[248:249], v[232:233], v[248:249]
	v_cvt_pk_bf16_f32 v150, v246, v247
	v_cvt_pk_bf16_f32 v151, v248, v249
	v_pk_fma_f32 v[112:113], v[112:113], v[202:203], v[162:163]
	v_pk_fma_f32 v[114:115], v[114:115], v[204:205], v[164:165]
	global_store_dwordx4 v145, v[112:115], s[26:27] offset:528
	v_mul_f32_e32 v161, v113, v113
	v_mul_f32_e32 v186, v115, v115
	v_fmac_f32_e32 v161, v112, v112
	v_fmac_f32_e32 v186, v114, v114
	v_add_f32_e32 v161, v161, v186
	v_add_f32_e32 v187, v187, v161
	v_pk_mul_f32 v[162:163], v[218:219], v[112:113]
	v_pk_mul_f32 v[164:165], v[220:221], v[114:115]
	v_pk_mul_f32 v[162:163], v[234:235], v[162:163]
	v_pk_mul_f32 v[164:165], v[236:237], v[164:165]
	v_cvt_pk_bf16_f32 v152, v162, v163
	v_cvt_pk_bf16_f32 v153, v164, v165
	global_store_dwordx4 v146, v[150:153], s[28:29] offset:256
	ds_bpermute_b32 v186, v148, v187
	s_add_u32 s26, s12, 0x0
	s_addc_u32 s27, s13, 0
	s_waitcnt lgkmcnt(0)
	v_add_f32_e32 v187, v187, v186
	ds_bpermute_b32 v186, v149, v187
	s_waitcnt lgkmcnt(0)
	v_add_f32_e32 v187, v187, v186
	s_and_saveexec_b64 s[28:29], s[2:3]
	global_atomic_add_f32 v147, v187, s[26:27]
	s_mov_b64 exec, s[28:29]
	s_add_u32 s0, s40, 0x20000
	s_addc_u32 s1, s41, 0
	global_load_dwordx4 v[238:241], v145, s[0:1] nt
	global_load_dwordx4 v[242:245], v145, s[0:1] offset:16 nt
	global_load_dwordx4 v[246:249], v145, s[0:1] offset:512 nt
	global_load_dwordx4 v[162:165], v145, s[0:1] offset:528 nt
	s_waitcnt vmcnt(11)
	s_add_u32 s26, s72, 0x10000
	s_addc_u32 s27, s73, 0
	s_add_u32 s28, s10, 0x8000
	s_addc_u32 s29, s11, 0
	v_pk_fma_f32 v[108:109], v[108:109], v[190:191], v[166:167]
	v_pk_fma_f32 v[110:111], v[110:111], v[192:193], v[168:169]
	global_store_dwordx4 v145, v[108:111], s[26:27]
	v_mul_f32_e32 v161, v109, v109
	v_mul_f32_e32 v186, v111, v111
	v_fmac_f32_e32 v161, v108, v108
	v_fmac_f32_e32 v186, v110, v110
	v_add_f32_e32 v187, v161, v186
	v_pk_mul_f32 v[166:167], v[206:207], v[108:109]
	v_pk_mul_f32 v[168:169], v[208:209], v[110:111]
	v_pk_mul_f32 v[166:167], v[222:223], v[166:167]
	v_pk_mul_f32 v[168:169], v[224:225], v[168:169]
	v_cvt_pk_bf16_f32 v182, v166, v167
	v_cvt_pk_bf16_f32 v183, v168, v169
	v_pk_fma_f32 v[104:105], v[104:105], v[194:195], v[170:171]
	v_pk_fma_f32 v[106:107], v[106:107], v[196:197], v[172:173]
	global_store_dwordx4 v145, v[104:107], s[26:27] offset:16
	v_mul_f32_e32 v161, v105, v105
	v_mul_f32_e32 v186, v107, v107
	v_fmac_f32_e32 v161, v104, v104
	v_fmac_f32_e32 v186, v106, v106
	v_add_f32_e32 v161, v161, v186
	v_add_f32_e32 v187, v187, v161
	v_pk_mul_f32 v[170:171], v[210:211], v[104:105]
	v_pk_mul_f32 v[172:173], v[212:213], v[106:107]
	v_pk_mul_f32 v[170:171], v[226:227], v[170:171]
	v_pk_mul_f32 v[172:173], v[228:229], v[172:173]
	v_cvt_pk_bf16_f32 v184, v170, v171
	v_cvt_pk_bf16_f32 v185, v172, v173
	global_store_dwordx4 v146, v[182:185], s[28:29]
	v_pk_fma_f32 v[100:101], v[100:101], v[198:199], v[174:175]
	v_pk_fma_f32 v[102:103], v[102:103], v[200:201], v[176:177]
	global_store_dwordx4 v145, v[100:103], s[26:27] offset:512
	v_mul_f32_e32 v161, v101, v101
	v_mul_f32_e32 v186, v103, v103
	v_fmac_f32_e32 v161, v100, v100
	v_fmac_f32_e32 v186, v102, v102
	v_add_f32_e32 v161, v161, v186
	v_add_f32_e32 v187, v187, v161
	v_pk_mul_f32 v[174:175], v[214:215], v[100:101]
	v_pk_mul_f32 v[176:177], v[216:217], v[102:103]
	v_pk_mul_f32 v[174:175], v[230:231], v[174:175]
	v_pk_mul_f32 v[176:177], v[232:233], v[176:177]
	v_cvt_pk_bf16_f32 v150, v174, v175
	v_cvt_pk_bf16_f32 v151, v176, v177
	v_pk_fma_f32 v[96:97], v[96:97], v[202:203], v[178:179]
	v_pk_fma_f32 v[98:99], v[98:99], v[204:205], v[180:181]
	global_store_dwordx4 v145, v[96:99], s[26:27] offset:528
	v_mul_f32_e32 v161, v97, v97
	v_mul_f32_e32 v186, v99, v99
	v_fmac_f32_e32 v161, v96, v96
	v_fmac_f32_e32 v186, v98, v98
	v_add_f32_e32 v161, v161, v186
	v_add_f32_e32 v187, v187, v161
	v_pk_mul_f32 v[178:179], v[218:219], v[96:97]
	v_pk_mul_f32 v[180:181], v[220:221], v[98:99]
	v_pk_mul_f32 v[178:179], v[234:235], v[178:179]
	v_pk_mul_f32 v[180:181], v[236:237], v[180:181]
	v_cvt_pk_bf16_f32 v152, v178, v179
	v_cvt_pk_bf16_f32 v153, v180, v181
	global_store_dwordx4 v146, v[150:153], s[28:29] offset:256
	ds_bpermute_b32 v186, v148, v187
	s_add_u32 s26, s12, 0x40
	s_addc_u32 s27, s13, 0
	s_waitcnt lgkmcnt(0)
	v_add_f32_e32 v187, v187, v186
	ds_bpermute_b32 v186, v149, v187
	s_waitcnt lgkmcnt(0)
	v_add_f32_e32 v187, v187, v186
	s_and_saveexec_b64 s[28:29], s[2:3]
	global_atomic_add_f32 v147, v187, s[26:27]
	s_mov_b64 exec, s[28:29]
	s_add_u32 s0, s40, 0x30000
	s_addc_u32 s1, s41, 0
	global_load_dwordx4 v[166:169], v145, s[0:1] nt
	global_load_dwordx4 v[170:173], v145, s[0:1] offset:16 nt
	global_load_dwordx4 v[174:177], v145, s[0:1] offset:512 nt
	global_load_dwordx4 v[178:181], v145, s[0:1] offset:528 nt
	s_waitcnt vmcnt(11)
	s_add_u32 s26, s72, 0x20000
	s_addc_u32 s27, s73, 0
	s_add_u32 s28, s10, 0x10000
	s_addc_u32 s29, s11, 0
	v_pk_fma_f32 v[92:93], v[92:93], v[190:191], v[238:239]
	v_pk_fma_f32 v[94:95], v[94:95], v[192:193], v[240:241]
	global_store_dwordx4 v145, v[92:95], s[26:27]
	v_mul_f32_e32 v161, v93, v93
	v_mul_f32_e32 v186, v95, v95
	v_fmac_f32_e32 v161, v92, v92
	v_fmac_f32_e32 v186, v94, v94
	v_add_f32_e32 v187, v161, v186
	v_pk_mul_f32 v[238:239], v[206:207], v[92:93]
	v_pk_mul_f32 v[240:241], v[208:209], v[94:95]
	v_pk_mul_f32 v[238:239], v[222:223], v[238:239]
	v_pk_mul_f32 v[240:241], v[224:225], v[240:241]
	v_cvt_pk_bf16_f32 v182, v238, v239
	v_cvt_pk_bf16_f32 v183, v240, v241
	v_pk_fma_f32 v[88:89], v[88:89], v[194:195], v[242:243]
	v_pk_fma_f32 v[90:91], v[90:91], v[196:197], v[244:245]
	global_store_dwordx4 v145, v[88:91], s[26:27] offset:16
	v_mul_f32_e32 v161, v89, v89
	v_mul_f32_e32 v186, v91, v91
	v_fmac_f32_e32 v161, v88, v88
	v_fmac_f32_e32 v186, v90, v90
	v_add_f32_e32 v161, v161, v186
	v_add_f32_e32 v187, v187, v161
	v_pk_mul_f32 v[242:243], v[210:211], v[88:89]
	v_pk_mul_f32 v[244:245], v[212:213], v[90:91]
	v_pk_mul_f32 v[242:243], v[226:227], v[242:243]
	v_pk_mul_f32 v[244:245], v[228:229], v[244:245]
	v_cvt_pk_bf16_f32 v184, v242, v243
	v_cvt_pk_bf16_f32 v185, v244, v245
	global_store_dwordx4 v146, v[182:185], s[28:29]
	v_pk_fma_f32 v[84:85], v[84:85], v[198:199], v[246:247]
	v_pk_fma_f32 v[86:87], v[86:87], v[200:201], v[248:249]
	global_store_dwordx4 v145, v[84:87], s[26:27] offset:512
	v_mul_f32_e32 v161, v85, v85
	v_mul_f32_e32 v186, v87, v87
	v_fmac_f32_e32 v161, v84, v84
	v_fmac_f32_e32 v186, v86, v86
	v_add_f32_e32 v161, v161, v186
	v_add_f32_e32 v187, v187, v161
	v_pk_mul_f32 v[246:247], v[214:215], v[84:85]
	v_pk_mul_f32 v[248:249], v[216:217], v[86:87]
	v_pk_mul_f32 v[246:247], v[230:231], v[246:247]
	v_pk_mul_f32 v[248:249], v[232:233], v[248:249]
	v_cvt_pk_bf16_f32 v150, v246, v247
	v_cvt_pk_bf16_f32 v151, v248, v249
	v_pk_fma_f32 v[80:81], v[80:81], v[202:203], v[162:163]
	v_pk_fma_f32 v[82:83], v[82:83], v[204:205], v[164:165]
	global_store_dwordx4 v145, v[80:83], s[26:27] offset:528
	v_mul_f32_e32 v161, v81, v81
	v_mul_f32_e32 v186, v83, v83
	v_fmac_f32_e32 v161, v80, v80
	v_fmac_f32_e32 v186, v82, v82
	v_add_f32_e32 v161, v161, v186
	v_add_f32_e32 v187, v187, v161
	v_pk_mul_f32 v[162:163], v[218:219], v[80:81]
	v_pk_mul_f32 v[164:165], v[220:221], v[82:83]
	v_pk_mul_f32 v[162:163], v[234:235], v[162:163]
	v_pk_mul_f32 v[164:165], v[236:237], v[164:165]
	v_cvt_pk_bf16_f32 v152, v162, v163
	v_cvt_pk_bf16_f32 v153, v164, v165
	global_store_dwordx4 v146, v[150:153], s[28:29] offset:256
	ds_bpermute_b32 v186, v148, v187
	s_add_u32 s26, s12, 0x80
	s_addc_u32 s27, s13, 0
	s_waitcnt lgkmcnt(0)
	v_add_f32_e32 v187, v187, v186
	ds_bpermute_b32 v186, v149, v187
	s_waitcnt lgkmcnt(0)
	v_add_f32_e32 v187, v187, v186
	s_and_saveexec_b64 s[28:29], s[2:3]
	global_atomic_add_f32 v147, v187, s[26:27]
	s_mov_b64 exec, s[28:29]
	s_add_u32 s0, s40, 0x80000
	s_addc_u32 s1, s41, 0
	global_load_dwordx4 v[238:241], v145, s[0:1] nt
	global_load_dwordx4 v[242:245], v145, s[0:1] offset:16 nt
	global_load_dwordx4 v[246:249], v145, s[0:1] offset:512 nt
	global_load_dwordx4 v[162:165], v145, s[0:1] offset:528 nt
	s_waitcnt vmcnt(11)
	s_add_u32 s26, s72, 0x30000
	s_addc_u32 s27, s73, 0
	s_add_u32 s28, s10, 0x18000
	s_addc_u32 s29, s11, 0
	v_pk_fma_f32 v[76:77], v[76:77], v[190:191], v[166:167]
	v_pk_fma_f32 v[78:79], v[78:79], v[192:193], v[168:169]
	global_store_dwordx4 v145, v[76:79], s[26:27]
	v_mul_f32_e32 v161, v77, v77
	v_mul_f32_e32 v186, v79, v79
	v_fmac_f32_e32 v161, v76, v76
	v_fmac_f32_e32 v186, v78, v78
	v_add_f32_e32 v187, v161, v186
	v_pk_mul_f32 v[166:167], v[206:207], v[76:77]
	v_pk_mul_f32 v[168:169], v[208:209], v[78:79]
	v_pk_mul_f32 v[166:167], v[222:223], v[166:167]
	v_pk_mul_f32 v[168:169], v[224:225], v[168:169]
	v_cvt_pk_bf16_f32 v182, v166, v167
	v_cvt_pk_bf16_f32 v183, v168, v169
	v_pk_fma_f32 v[72:73], v[72:73], v[194:195], v[170:171]
	v_pk_fma_f32 v[74:75], v[74:75], v[196:197], v[172:173]
	global_store_dwordx4 v145, v[72:75], s[26:27] offset:16
	v_mul_f32_e32 v161, v73, v73
	v_mul_f32_e32 v186, v75, v75
	v_fmac_f32_e32 v161, v72, v72
	v_fmac_f32_e32 v186, v74, v74
	v_add_f32_e32 v161, v161, v186
	v_add_f32_e32 v187, v187, v161
	v_pk_mul_f32 v[170:171], v[210:211], v[72:73]
	v_pk_mul_f32 v[172:173], v[212:213], v[74:75]
	v_pk_mul_f32 v[170:171], v[226:227], v[170:171]
	v_pk_mul_f32 v[172:173], v[228:229], v[172:173]
	v_cvt_pk_bf16_f32 v184, v170, v171
	v_cvt_pk_bf16_f32 v185, v172, v173
	global_store_dwordx4 v146, v[182:185], s[28:29]
	v_pk_fma_f32 v[68:69], v[68:69], v[198:199], v[174:175]
	v_pk_fma_f32 v[70:71], v[70:71], v[200:201], v[176:177]
	global_store_dwordx4 v145, v[68:71], s[26:27] offset:512
	v_mul_f32_e32 v161, v69, v69
	v_mul_f32_e32 v186, v71, v71
	v_fmac_f32_e32 v161, v68, v68
	v_fmac_f32_e32 v186, v70, v70
	v_add_f32_e32 v161, v161, v186
	v_add_f32_e32 v187, v187, v161
	v_pk_mul_f32 v[174:175], v[214:215], v[68:69]
	v_pk_mul_f32 v[176:177], v[216:217], v[70:71]
	v_pk_mul_f32 v[174:175], v[230:231], v[174:175]
	v_pk_mul_f32 v[176:177], v[232:233], v[176:177]
	v_cvt_pk_bf16_f32 v150, v174, v175
	v_cvt_pk_bf16_f32 v151, v176, v177
	v_pk_fma_f32 v[64:65], v[64:65], v[202:203], v[178:179]
	v_pk_fma_f32 v[66:67], v[66:67], v[204:205], v[180:181]
	global_store_dwordx4 v145, v[64:67], s[26:27] offset:528
	v_mul_f32_e32 v161, v65, v65
	v_mul_f32_e32 v186, v67, v67
	v_fmac_f32_e32 v161, v64, v64
	v_fmac_f32_e32 v186, v66, v66
	v_add_f32_e32 v161, v161, v186
	v_add_f32_e32 v187, v187, v161
	v_pk_mul_f32 v[178:179], v[218:219], v[64:65]
	v_pk_mul_f32 v[180:181], v[220:221], v[66:67]
	v_pk_mul_f32 v[178:179], v[234:235], v[178:179]
	v_pk_mul_f32 v[180:181], v[236:237], v[180:181]
	v_cvt_pk_bf16_f32 v152, v178, v179
	v_cvt_pk_bf16_f32 v153, v180, v181
	global_store_dwordx4 v146, v[150:153], s[28:29] offset:256
	ds_bpermute_b32 v186, v148, v187
	s_add_u32 s26, s12, 0xc0
	s_addc_u32 s27, s13, 0
	s_waitcnt lgkmcnt(0)
	v_add_f32_e32 v187, v187, v186
	ds_bpermute_b32 v186, v149, v187
	s_waitcnt lgkmcnt(0)
	v_add_f32_e32 v187, v187, v186
	s_and_saveexec_b64 s[28:29], s[2:3]
	global_atomic_add_f32 v147, v187, s[26:27]
	s_mov_b64 exec, s[28:29]
	s_add_u32 s0, s40, 0x90000
	s_addc_u32 s1, s41, 0
	global_load_dwordx4 v[166:169], v145, s[0:1] nt
	global_load_dwordx4 v[170:173], v145, s[0:1] offset:16 nt
	global_load_dwordx4 v[174:177], v145, s[0:1] offset:512 nt
	global_load_dwordx4 v[178:181], v145, s[0:1] offset:528 nt
	s_waitcnt vmcnt(11)
	s_add_u32 s26, s72, 0x80000
	s_addc_u32 s27, s73, 0
	s_add_u32 s28, s10, 0x40000
	s_addc_u32 s29, s11, 0
	v_pk_fma_f32 v[60:61], v[60:61], v[190:191], v[238:239]
	v_pk_fma_f32 v[62:63], v[62:63], v[192:193], v[240:241]
	global_store_dwordx4 v145, v[60:63], s[26:27]
	v_mul_f32_e32 v161, v61, v61
	v_mul_f32_e32 v186, v63, v63
	v_fmac_f32_e32 v161, v60, v60
	v_fmac_f32_e32 v186, v62, v62
	v_add_f32_e32 v187, v161, v186
	v_pk_mul_f32 v[238:239], v[206:207], v[60:61]
	v_pk_mul_f32 v[240:241], v[208:209], v[62:63]
	v_pk_mul_f32 v[238:239], v[222:223], v[238:239]
	v_pk_mul_f32 v[240:241], v[224:225], v[240:241]
	v_cvt_pk_bf16_f32 v182, v238, v239
	v_cvt_pk_bf16_f32 v183, v240, v241
	v_pk_fma_f32 v[56:57], v[56:57], v[194:195], v[242:243]
	v_pk_fma_f32 v[58:59], v[58:59], v[196:197], v[244:245]
	global_store_dwordx4 v145, v[56:59], s[26:27] offset:16
	v_mul_f32_e32 v161, v57, v57
	v_mul_f32_e32 v186, v59, v59
	v_fmac_f32_e32 v161, v56, v56
	v_fmac_f32_e32 v186, v58, v58
	v_add_f32_e32 v161, v161, v186
	v_add_f32_e32 v187, v187, v161
	v_pk_mul_f32 v[242:243], v[210:211], v[56:57]
	v_pk_mul_f32 v[244:245], v[212:213], v[58:59]
	v_pk_mul_f32 v[242:243], v[226:227], v[242:243]
	v_pk_mul_f32 v[244:245], v[228:229], v[244:245]
	v_cvt_pk_bf16_f32 v184, v242, v243
	v_cvt_pk_bf16_f32 v185, v244, v245
	global_store_dwordx4 v146, v[182:185], s[28:29]
	v_pk_fma_f32 v[52:53], v[52:53], v[198:199], v[246:247]
	v_pk_fma_f32 v[54:55], v[54:55], v[200:201], v[248:249]
	global_store_dwordx4 v145, v[52:55], s[26:27] offset:512
	v_mul_f32_e32 v161, v53, v53
	v_mul_f32_e32 v186, v55, v55
	v_fmac_f32_e32 v161, v52, v52
	v_fmac_f32_e32 v186, v54, v54
	v_add_f32_e32 v161, v161, v186
	v_add_f32_e32 v187, v187, v161
	v_pk_mul_f32 v[246:247], v[214:215], v[52:53]
	v_pk_mul_f32 v[248:249], v[216:217], v[54:55]
	v_pk_mul_f32 v[246:247], v[230:231], v[246:247]
	v_pk_mul_f32 v[248:249], v[232:233], v[248:249]
	v_cvt_pk_bf16_f32 v150, v246, v247
	v_cvt_pk_bf16_f32 v151, v248, v249
	v_pk_fma_f32 v[48:49], v[48:49], v[202:203], v[162:163]
	v_pk_fma_f32 v[50:51], v[50:51], v[204:205], v[164:165]
	global_store_dwordx4 v145, v[48:51], s[26:27] offset:528
	v_mul_f32_e32 v161, v49, v49
	v_mul_f32_e32 v186, v51, v51
	v_fmac_f32_e32 v161, v48, v48
	v_fmac_f32_e32 v186, v50, v50
	v_add_f32_e32 v161, v161, v186
	v_add_f32_e32 v187, v187, v161
	v_pk_mul_f32 v[162:163], v[218:219], v[48:49]
	v_pk_mul_f32 v[164:165], v[220:221], v[50:51]
	v_pk_mul_f32 v[162:163], v[234:235], v[162:163]
	v_pk_mul_f32 v[164:165], v[236:237], v[164:165]
	v_cvt_pk_bf16_f32 v152, v162, v163
	v_cvt_pk_bf16_f32 v153, v164, v165
	global_store_dwordx4 v146, v[150:153], s[28:29] offset:256
	ds_bpermute_b32 v186, v148, v187
	s_add_u32 s26, s12, 0x200
	s_addc_u32 s27, s13, 0
	s_waitcnt lgkmcnt(0)
	v_add_f32_e32 v187, v187, v186
	ds_bpermute_b32 v186, v149, v187
	s_waitcnt lgkmcnt(0)
	v_add_f32_e32 v187, v187, v186
	s_and_saveexec_b64 s[28:29], s[2:3]
	global_atomic_add_f32 v147, v187, s[26:27]
	s_mov_b64 exec, s[28:29]
	s_add_u32 s0, s40, 0xa0000
	s_addc_u32 s1, s41, 0
	global_load_dwordx4 v[238:241], v145, s[0:1] nt
	global_load_dwordx4 v[242:245], v145, s[0:1] offset:16 nt
	global_load_dwordx4 v[246:249], v145, s[0:1] offset:512 nt
	global_load_dwordx4 v[162:165], v145, s[0:1] offset:528 nt
	s_waitcnt vmcnt(11)
	s_add_u32 s26, s72, 0x90000
	s_addc_u32 s27, s73, 0
	s_add_u32 s28, s10, 0x48000
	s_addc_u32 s29, s11, 0
	v_pk_fma_f32 v[44:45], v[44:45], v[190:191], v[166:167]
	v_pk_fma_f32 v[46:47], v[46:47], v[192:193], v[168:169]
	global_store_dwordx4 v145, v[44:47], s[26:27]
	v_mul_f32_e32 v161, v45, v45
	v_mul_f32_e32 v186, v47, v47
	v_fmac_f32_e32 v161, v44, v44
	v_fmac_f32_e32 v186, v46, v46
	v_add_f32_e32 v187, v161, v186
	v_pk_mul_f32 v[166:167], v[206:207], v[44:45]
	v_pk_mul_f32 v[168:169], v[208:209], v[46:47]
	v_pk_mul_f32 v[166:167], v[222:223], v[166:167]
	v_pk_mul_f32 v[168:169], v[224:225], v[168:169]
	v_cvt_pk_bf16_f32 v182, v166, v167
	v_cvt_pk_bf16_f32 v183, v168, v169
	v_pk_fma_f32 v[40:41], v[40:41], v[194:195], v[170:171]
	v_pk_fma_f32 v[42:43], v[42:43], v[196:197], v[172:173]
	global_store_dwordx4 v145, v[40:43], s[26:27] offset:16
	v_mul_f32_e32 v161, v41, v41
	v_mul_f32_e32 v186, v43, v43
	v_fmac_f32_e32 v161, v40, v40
	v_fmac_f32_e32 v186, v42, v42
	v_add_f32_e32 v161, v161, v186
	v_add_f32_e32 v187, v187, v161
	v_pk_mul_f32 v[170:171], v[210:211], v[40:41]
	v_pk_mul_f32 v[172:173], v[212:213], v[42:43]
	v_pk_mul_f32 v[170:171], v[226:227], v[170:171]
	v_pk_mul_f32 v[172:173], v[228:229], v[172:173]
	v_cvt_pk_bf16_f32 v184, v170, v171
	v_cvt_pk_bf16_f32 v185, v172, v173
	global_store_dwordx4 v146, v[182:185], s[28:29]
	v_pk_fma_f32 v[36:37], v[36:37], v[198:199], v[174:175]
	v_pk_fma_f32 v[38:39], v[38:39], v[200:201], v[176:177]
	global_store_dwordx4 v145, v[36:39], s[26:27] offset:512
	v_mul_f32_e32 v161, v37, v37
	v_mul_f32_e32 v186, v39, v39
	v_fmac_f32_e32 v161, v36, v36
	v_fmac_f32_e32 v186, v38, v38
	v_add_f32_e32 v161, v161, v186
	v_add_f32_e32 v187, v187, v161
	v_pk_mul_f32 v[174:175], v[214:215], v[36:37]
	v_pk_mul_f32 v[176:177], v[216:217], v[38:39]
	v_pk_mul_f32 v[174:175], v[230:231], v[174:175]
	v_pk_mul_f32 v[176:177], v[232:233], v[176:177]
	v_cvt_pk_bf16_f32 v150, v174, v175
	v_cvt_pk_bf16_f32 v151, v176, v177
	v_pk_fma_f32 v[32:33], v[32:33], v[202:203], v[178:179]
	v_pk_fma_f32 v[34:35], v[34:35], v[204:205], v[180:181]
	global_store_dwordx4 v145, v[32:35], s[26:27] offset:528
	v_mul_f32_e32 v161, v33, v33
	v_mul_f32_e32 v186, v35, v35
	v_fmac_f32_e32 v161, v32, v32
	v_fmac_f32_e32 v186, v34, v34
	v_add_f32_e32 v161, v161, v186
	v_add_f32_e32 v187, v187, v161
	v_pk_mul_f32 v[178:179], v[218:219], v[32:33]
	v_pk_mul_f32 v[180:181], v[220:221], v[34:35]
	v_pk_mul_f32 v[178:179], v[234:235], v[178:179]
	v_pk_mul_f32 v[180:181], v[236:237], v[180:181]
	v_cvt_pk_bf16_f32 v152, v178, v179
	v_cvt_pk_bf16_f32 v153, v180, v181
	global_store_dwordx4 v146, v[150:153], s[28:29] offset:256
	ds_bpermute_b32 v186, v148, v187
	s_add_u32 s26, s12, 0x240
	s_addc_u32 s27, s13, 0
	s_waitcnt lgkmcnt(0)
	v_add_f32_e32 v187, v187, v186
	ds_bpermute_b32 v186, v149, v187
	s_waitcnt lgkmcnt(0)
	v_add_f32_e32 v187, v187, v186
	s_and_saveexec_b64 s[28:29], s[2:3]
	global_atomic_add_f32 v147, v187, s[26:27]
	s_mov_b64 exec, s[28:29]
	s_add_u32 s0, s40, 0xb0000
	s_addc_u32 s1, s41, 0
	global_load_dwordx4 v[166:169], v145, s[0:1] nt
	global_load_dwordx4 v[170:173], v145, s[0:1] offset:16 nt
	global_load_dwordx4 v[174:177], v145, s[0:1] offset:512 nt
	global_load_dwordx4 v[178:181], v145, s[0:1] offset:528 nt
	s_waitcnt vmcnt(11)
	s_add_u32 s26, s72, 0xa0000
	s_addc_u32 s27, s73, 0
	s_add_u32 s28, s10, 0x50000
	s_addc_u32 s29, s11, 0
	v_pk_fma_f32 v[28:29], v[28:29], v[190:191], v[238:239]
	v_pk_fma_f32 v[30:31], v[30:31], v[192:193], v[240:241]
	global_store_dwordx4 v145, v[28:31], s[26:27]
	v_mul_f32_e32 v161, v29, v29
	v_mul_f32_e32 v186, v31, v31
	v_fmac_f32_e32 v161, v28, v28
	v_fmac_f32_e32 v186, v30, v30
	v_add_f32_e32 v187, v161, v186
	v_pk_mul_f32 v[238:239], v[206:207], v[28:29]
	v_pk_mul_f32 v[240:241], v[208:209], v[30:31]
	v_pk_mul_f32 v[238:239], v[222:223], v[238:239]
	v_pk_mul_f32 v[240:241], v[224:225], v[240:241]
	v_cvt_pk_bf16_f32 v182, v238, v239
	v_cvt_pk_bf16_f32 v183, v240, v241
	v_pk_fma_f32 v[24:25], v[24:25], v[194:195], v[242:243]
	v_pk_fma_f32 v[26:27], v[26:27], v[196:197], v[244:245]
	global_store_dwordx4 v145, v[24:27], s[26:27] offset:16
	v_mul_f32_e32 v161, v25, v25
	v_mul_f32_e32 v186, v27, v27
	v_fmac_f32_e32 v161, v24, v24
	v_fmac_f32_e32 v186, v26, v26
	v_add_f32_e32 v161, v161, v186
	v_add_f32_e32 v187, v187, v161
	v_pk_mul_f32 v[242:243], v[210:211], v[24:25]
	v_pk_mul_f32 v[244:245], v[212:213], v[26:27]
	v_pk_mul_f32 v[242:243], v[226:227], v[242:243]
	v_pk_mul_f32 v[244:245], v[228:229], v[244:245]
	v_cvt_pk_bf16_f32 v184, v242, v243
	v_cvt_pk_bf16_f32 v185, v244, v245
	global_store_dwordx4 v146, v[182:185], s[28:29]
	v_pk_fma_f32 v[20:21], v[20:21], v[198:199], v[246:247]
	v_pk_fma_f32 v[22:23], v[22:23], v[200:201], v[248:249]
	global_store_dwordx4 v145, v[20:23], s[26:27] offset:512
	v_mul_f32_e32 v161, v21, v21
	v_mul_f32_e32 v186, v23, v23
	v_fmac_f32_e32 v161, v20, v20
	v_fmac_f32_e32 v186, v22, v22
	v_add_f32_e32 v161, v161, v186
	v_add_f32_e32 v187, v187, v161
	v_pk_mul_f32 v[246:247], v[214:215], v[20:21]
	v_pk_mul_f32 v[248:249], v[216:217], v[22:23]
	v_pk_mul_f32 v[246:247], v[230:231], v[246:247]
	v_pk_mul_f32 v[248:249], v[232:233], v[248:249]
	v_cvt_pk_bf16_f32 v150, v246, v247
	v_cvt_pk_bf16_f32 v151, v248, v249
	v_pk_fma_f32 v[16:17], v[16:17], v[202:203], v[162:163]
	v_pk_fma_f32 v[18:19], v[18:19], v[204:205], v[164:165]
	global_store_dwordx4 v145, v[16:19], s[26:27] offset:528
	v_mul_f32_e32 v161, v17, v17
	v_mul_f32_e32 v186, v19, v19
	v_fmac_f32_e32 v161, v16, v16
	v_fmac_f32_e32 v186, v18, v18
	v_add_f32_e32 v161, v161, v186
	v_add_f32_e32 v187, v187, v161
	v_pk_mul_f32 v[162:163], v[218:219], v[16:17]
	v_pk_mul_f32 v[164:165], v[220:221], v[18:19]
	v_pk_mul_f32 v[162:163], v[234:235], v[162:163]
	v_pk_mul_f32 v[164:165], v[236:237], v[164:165]
	v_cvt_pk_bf16_f32 v152, v162, v163
	v_cvt_pk_bf16_f32 v153, v164, v165
	global_store_dwordx4 v146, v[150:153], s[28:29] offset:256
	ds_bpermute_b32 v186, v148, v187
	s_add_u32 s26, s12, 0x280
	s_addc_u32 s27, s13, 0
	s_waitcnt lgkmcnt(0)
	v_add_f32_e32 v187, v187, v186
	ds_bpermute_b32 v186, v149, v187
	s_waitcnt lgkmcnt(0)
	v_add_f32_e32 v187, v187, v186
	s_and_saveexec_b64 s[28:29], s[2:3]
	global_atomic_add_f32 v147, v187, s[26:27]
	s_mov_b64 exec, s[28:29]
	s_waitcnt vmcnt(7)
	s_add_u32 s26, s72, 0xb0000
	s_addc_u32 s27, s73, 0
	s_add_u32 s28, s10, 0x58000
	s_addc_u32 s29, s11, 0
	v_pk_fma_f32 v[12:13], v[12:13], v[190:191], v[166:167]
	v_pk_fma_f32 v[14:15], v[14:15], v[192:193], v[168:169]
	global_store_dwordx4 v145, v[12:15], s[26:27]
	v_mul_f32_e32 v161, v13, v13
	v_mul_f32_e32 v186, v15, v15
	v_fmac_f32_e32 v161, v12, v12
	v_fmac_f32_e32 v186, v14, v14
	v_add_f32_e32 v187, v161, v186
	v_pk_mul_f32 v[166:167], v[206:207], v[12:13]
	v_pk_mul_f32 v[168:169], v[208:209], v[14:15]
	v_pk_mul_f32 v[166:167], v[222:223], v[166:167]
	v_pk_mul_f32 v[168:169], v[224:225], v[168:169]
	v_cvt_pk_bf16_f32 v182, v166, v167
	v_cvt_pk_bf16_f32 v183, v168, v169
	v_pk_fma_f32 v[8:9], v[8:9], v[194:195], v[170:171]
	v_pk_fma_f32 v[10:11], v[10:11], v[196:197], v[172:173]
	global_store_dwordx4 v145, v[8:11], s[26:27] offset:16
	v_mul_f32_e32 v161, v9, v9
	v_mul_f32_e32 v186, v11, v11
	v_fmac_f32_e32 v161, v8, v8
	v_fmac_f32_e32 v186, v10, v10
	v_add_f32_e32 v161, v161, v186
	v_add_f32_e32 v187, v187, v161
	v_pk_mul_f32 v[170:171], v[210:211], v[8:9]
	v_pk_mul_f32 v[172:173], v[212:213], v[10:11]
	v_pk_mul_f32 v[170:171], v[226:227], v[170:171]
	v_pk_mul_f32 v[172:173], v[228:229], v[172:173]
	v_cvt_pk_bf16_f32 v184, v170, v171
	v_cvt_pk_bf16_f32 v185, v172, v173
	global_store_dwordx4 v146, v[182:185], s[28:29]
	v_pk_fma_f32 v[4:5], v[4:5], v[198:199], v[174:175]
	v_pk_fma_f32 v[6:7], v[6:7], v[200:201], v[176:177]
	global_store_dwordx4 v145, v[4:7], s[26:27] offset:512
	v_mul_f32_e32 v161, v5, v5
	v_mul_f32_e32 v186, v7, v7
	v_fmac_f32_e32 v161, v4, v4
	v_fmac_f32_e32 v186, v6, v6
	v_add_f32_e32 v161, v161, v186
	v_add_f32_e32 v187, v187, v161
	v_pk_mul_f32 v[174:175], v[214:215], v[4:5]
	v_pk_mul_f32 v[176:177], v[216:217], v[6:7]
	v_pk_mul_f32 v[174:175], v[230:231], v[174:175]
	v_pk_mul_f32 v[176:177], v[232:233], v[176:177]
	v_cvt_pk_bf16_f32 v150, v174, v175
	v_cvt_pk_bf16_f32 v151, v176, v177
	v_pk_fma_f32 v[0:1], v[0:1], v[202:203], v[178:179]
	v_pk_fma_f32 v[2:3], v[2:3], v[204:205], v[180:181]
	global_store_dwordx4 v145, v[0:3], s[26:27] offset:528
	v_mul_f32_e32 v161, v1, v1
	v_mul_f32_e32 v186, v3, v3
	v_fmac_f32_e32 v161, v0, v0
	v_fmac_f32_e32 v186, v2, v2
	v_add_f32_e32 v161, v161, v186
	v_add_f32_e32 v187, v187, v161
	v_pk_mul_f32 v[178:179], v[218:219], v[0:1]
	v_pk_mul_f32 v[180:181], v[220:221], v[2:3]
	v_pk_mul_f32 v[178:179], v[234:235], v[178:179]
	v_pk_mul_f32 v[180:181], v[236:237], v[180:181]
	v_cvt_pk_bf16_f32 v152, v178, v179
	v_cvt_pk_bf16_f32 v153, v180, v181
	global_store_dwordx4 v146, v[150:153], s[28:29] offset:256
	ds_bpermute_b32 v186, v148, v187
	s_add_u32 s26, s12, 0x2c0
	s_addc_u32 s27, s13, 0
	s_waitcnt lgkmcnt(0)
	v_add_f32_e32 v187, v187, v186
	ds_bpermute_b32 v186, v149, v187
	s_waitcnt lgkmcnt(0)
	v_add_f32_e32 v187, v187, v186
	s_and_saveexec_b64 s[28:29], s[2:3]
	global_atomic_add_f32 v147, v187, s[26:27]
	s_mov_b64 exec, s[28:29]
	s_andn2_b64 vcc, exec, s[4:5]
	s_mov_b64 s[4:5], -1
	s_cbranch_vccnz .LBB0_583
	s_andn2_b64 vcc, exec, s[8:9]
	s_cbranch_vccnz .LBB0_582
	s_barrier
	s_branch .LBB0_582
